# write-through (sc1) stores for the now line-contiguous FFT output and channel-DFT output, which precede grid barriers
# speedup vs baseline: 1.0214x; 1.0029x over previous
; __device__ __forceinline__ unsigned cvt_pk_bf16(float lo, float hi) { f32x2_t v = {lo, hi}; bf16x2_t b = __builtin_convertvector(v, bf16x2_t); return __builtin_bit_cast(unsigned, b); }
; __device__ __forceinline__ void row_rs8(const float* ssq, int row0, int fq, float (&rr)[2][4]) {
;     float v[2][4][4];
; #pragma unroll
;     for (int ai = 0; ai < 2; ++ai)
; #pragma unroll
;         for (int m = 0; m < 4; ++m) { const float* p = ssq + (size_t)(4 * fq) * 16384 + row0 + ai * HALF + m * 16;
; #pragma unroll
;             for (int k = 0; k < 4; ++k) v[ai][m][k] = ld_agent(p + k * 16384); }
; #pragma unroll
;     for (int ai = 0; ai < 2; ++ai)
; #pragma unroll
;         for (int m = 0; m < 4; ++m) { float s = (v[ai][m][0] + v[ai][m][1]) + (v[ai][m][2] + v[ai][m][3]);
;             s += __shfl_xor(s, 16); s += __shfl_xor(s, 32); rr[ai][m] = __builtin_amdgcn_rsqf(s * (1.0f / 1024.0f) + RMS_EPS); }
; }
;     __device__ __forceinline__ void operator()(const f32x4 (&acc)[2][2][4][2], const Unit& u, int wr, int wc, int fr, int fq) const {
;         const int row0 = u.pm * BM + wr * 64 + fr, col0 = u.pn * BM + wc * 32 + 8 * fq; float rr[2][4]; row_rs8(ssq, row0, fq, rr);
; #pragma unroll
;         for (int ai = 0; ai < 2; ++ai)
; #pragma unroll
;             for (int m = 0; m < 4; ++m) { const int row = row0 + ai * HALF + m * 16; const float r = rr[ai][m];
; #pragma unroll
;                 for (int bj = 0; bj < 2; ++bj) { const f32x4 v0 = acc[ai][bj][m][0] * r, v1 = acc[ai][bj][m][1] * r;
;                     u32x4 w; w.x = cvt_pk_bf16(v0[0], v0[1]); w.y = cvt_pk_bf16(v0[2], v0[3]); w.z = cvt_pk_bf16(v1[0], v1[1]); w.w = cvt_pk_bf16(v1[2], v1[3]);
;                     *(u32x4*)(O + ((size_t)((row >> 13) * (ldc >> 3) + ((col0 + bj * HALF) >> 3)) * 8192 + (row & 8191)) * 8) = w; } }
.LBB0_132:
	v_mov_b32_e32 v144, v153
	s_lshl_b32 s6, s21, 8
	s_add_i32 s6, s6, s15
	v_add_u32_e32 v144, s6, v144
	v_ashrrev_i32_e32 v145, 31, v144
	v_lshl_add_u64 v[156:157], v[144:145], 2, v[138:139]
	v_add_co_u32_e32 v162, vcc, 0x10000, v156
	global_load_dword v168, v[156:157], off
	s_nop 0
	v_addc_co_u32_e32 v163, vcc, 0, v157, vcc
	v_add_co_u32_e32 v180, vcc, 0x20000, v156
	global_load_dword v170, v[162:163], off
	s_nop 0
	v_addc_co_u32_e32 v181, vcc, 0, v157, vcc
	v_add_co_u32_e32 v182, vcc, 0x30000, v156
	global_load_dword v169, v[180:181], off
	s_nop 0
	v_addc_co_u32_e32 v183, vcc, 0, v157, vcc
	global_load_dword v171, v[182:183], off
	global_load_dword v184, v[156:157], off offset:64
	global_load_dword v186, v[162:163], off offset:64
	global_load_dword v185, v[180:181], off offset:64
	global_load_dword v187, v[182:183], off offset:64
	global_load_dword v150, v[156:157], off offset:128
	global_load_dword v188, v[162:163], off offset:128
	global_load_dword v151, v[180:181], off offset:128
	global_load_dword v189, v[182:183], off offset:128
	global_load_dword v148, v[156:157], off offset:192
	global_load_dword v176, v[162:163], off offset:192
	global_load_dword v149, v[180:181], off offset:192
	global_load_dword v177, v[182:183], off offset:192
	global_load_dword v146, v[156:157], off offset:512
	global_load_dword v174, v[162:163], off offset:512
	global_load_dword v147, v[180:181], off offset:512
	global_load_dword v175, v[182:183], off offset:512
	global_load_dword v160, v[156:157], off offset:576
	global_load_dword v172, v[162:163], off offset:576
	global_load_dword v161, v[180:181], off offset:576
	global_load_dword v173, v[182:183], off offset:576
	global_load_dword v154, v[156:157], off offset:640
	global_load_dword v164, v[162:163], off offset:640
	global_load_dword v155, v[180:181], off offset:640
	global_load_dword v165, v[182:183], off offset:640
	s_nop 0
	global_load_dword v156, v[156:157], off offset:704
	s_nop 0
	global_load_dword v162, v[162:163], off offset:704
	s_nop 0
	global_load_dword v157, v[180:181], off offset:704
	global_load_dword v163, v[182:183], off offset:704
	v_and_b32_e32 v152, 64, v242
	v_xor_b32_e32 v145, 16, v242
	v_add_u32_e32 v152, 64, v152
	v_cmp_lt_i32_e32 vcc, v145, v152
	v_xor_b32_e32 v158, 32, v242
	v_lshl_or_b32 v166, s20, 8, v178
	v_cndmask_b32_e32 v145, v242, v145, vcc
	v_lshlrev_b32_e32 v145, 2, v145
	v_cmp_lt_i32_e32 vcc, v158, v152
	s_mov_b64 s[6:7], -1
	s_waitcnt vmcnt(0)
	v_pk_add_f32 v[150:151], v[150:151], v[188:189]
	v_cndmask_b32_e32 v152, v242, v158, vcc
	v_lshlrev_b32_e32 v180, 2, v152
	v_add_f32_e32 v150, v150, v151
	v_pk_add_f32 v[148:149], v[148:149], v[176:177]
	ds_bpermute_b32 v151, v145, v150
	v_add_f32_e32 v148, v148, v149
	ds_bpermute_b32 v149, v145, v148
	v_pk_add_f32 v[146:147], v[146:147], v[174:175]
	s_and_b64 vcc, exec, s[38:39]
	v_add_f32_e32 v146, v146, v147
	ds_bpermute_b32 v147, v145, v146
	s_waitcnt lgkmcnt(0)
	v_add_f32_e32 v148, v148, v149
	ds_bpermute_b32 v149, v180, v148
	v_pk_add_f32 v[160:161], v[160:161], v[172:173]
	v_add_f32_e32 v150, v150, v151
	v_add_f32_e32 v146, v146, v147
	ds_bpermute_b32 v147, v180, v146
	s_waitcnt lgkmcnt(1)
	v_add_f32_e32 v148, v148, v149
	v_pk_add_f32 v[168:169], v[168:169], v[170:171]
	v_pk_add_f32 v[154:155], v[154:155], v[164:165]
	v_add_f32_e32 v152, v168, v169
	s_waitcnt lgkmcnt(0)
	v_add_f32_e32 v146, v146, v147
	v_add_f32_e32 v147, v160, v161
	ds_bpermute_b32 v149, v145, v147
	ds_bpermute_b32 v158, v145, v152
	v_pk_add_f32 v[168:169], v[184:185], v[186:187]
	v_pk_add_f32 v[156:157], v[156:157], v[162:163]
	ds_bpermute_b32 v151, v180, v150
	s_waitcnt lgkmcnt(2)
	v_add_f32_e32 v147, v147, v149
	ds_bpermute_b32 v149, v180, v147
	s_waitcnt lgkmcnt(2)
	v_add_f32_e32 v152, v152, v158
	ds_bpermute_b32 v158, v180, v152
	s_waitcnt lgkmcnt(2)
	v_add_f32_e32 v150, v150, v151
	v_fmamk_f32 v150, v150, 0x3a800000, v1
	s_waitcnt lgkmcnt(1)
	v_add_f32_e32 v147, v147, v149
	v_fmamk_f32 v147, v147, 0x3a800000, v1
	v_rsq_f32_e32 v160, v147
	v_add_f32_e32 v147, v154, v155
	ds_bpermute_b32 v149, v145, v147
	s_waitcnt lgkmcnt(1)
	v_add_f32_e32 v152, v152, v158
	v_fmamk_f32 v152, v152, 0x3a800000, v1
	v_rsq_f32_e32 v158, v152
	v_add_f32_e32 v152, v168, v169
	s_waitcnt lgkmcnt(0)
	v_add_f32_e32 v147, v147, v149
	ds_bpermute_b32 v149, v180, v147
	ds_bpermute_b32 v168, v145, v152
	v_pk_mul_f32 v[126:127], v[126:127], v[158:159] op_sel_hi:[1,0]
	v_pk_mul_f32 v[128:129], v[128:129], v[158:159] op_sel_hi:[1,0]
	v_pk_mul_f32 v[162:163], v[124:125], v[158:159] op_sel_hi:[1,0]
	s_waitcnt lgkmcnt(1)
	v_add_f32_e32 v147, v147, v149
	v_fmamk_f32 v147, v147, 0x3a800000, v1
	v_rsq_f32_e32 v154, v147
	v_add_f32_e32 v147, v156, v157
	ds_bpermute_b32 v145, v145, v147
	v_pk_mul_f32 v[124:125], v[122:123], v[158:159] op_sel_hi:[1,0]
	v_cvt_pk_bf16_f32 v122, v126, v127
	v_ashrrev_i32_e32 v126, 6, v144
	s_waitcnt lgkmcnt(1)
	v_add_f32_e32 v152, v152, v168
	s_waitcnt lgkmcnt(0)
	v_add_f32_e32 v145, v147, v145
	ds_bpermute_b32 v147, v180, v145
	v_cvt_pk_bf16_f32 v123, v128, v129
	v_and_b32_e32 v128, 0xffffff80, v126
	v_ashrrev_i32_e32 v129, 3, v166
	ds_bpermute_b32 v168, v180, v152
	s_waitcnt lgkmcnt(1)
	v_add_f32_e32 v145, v145, v147
	v_add_u32_e32 v126, v128, v129
	v_fmamk_f32 v145, v145, 0x3a800000, v1
	v_ashrrev_i32_e32 v127, 31, v126
	v_rsq_f32_e32 v156, v145
	v_lshlrev_b64 v[126:127], 17, v[126:127]
	v_lshlrev_b32_e32 v145, 4, v144
	v_lshl_add_u64 v[126:127], s[56:57], 0, v[126:127]
	v_and_b32_e32 v166, 0x1fff0, v145
	v_cvt_pk_bf16_f32 v124, v124, v125
	v_cvt_pk_bf16_f32 v125, v162, v163
	v_lshl_add_u64 v[126:127], v[126:127], 0, v[166:167]
	v_pk_mul_f32 v[120:121], v[120:121], v[158:159] op_sel_hi:[1,0]
	s_waitcnt lgkmcnt(0)
; __device__ __forceinline__ unsigned cvt_pk_bf16(float lo, float hi) { f32x2_t v = {lo, hi}; bf16x2_t b = __builtin_convertvector(v, bf16x2_t); return __builtin_bit_cast(unsigned, b); }
;     __device__ __forceinline__ void operator()(const f32x4 (&acc)[2][2][4][2], const Unit& u, int wr, int wc, int fr, int fq) const {
;     ...
;             for (int m = 0; m < 4; ++m) { const int row = row0 + ai * HALF + m * 16; const float r = rr[ai][m];
; #pragma unroll
;                 for (int bj = 0; bj < 2; ++bj) { const f32x4 v0 = acc[ai][bj][m][0] * r, v1 = acc[ai][bj][m][1] * r;
;                     u32x4 w; w.x = cvt_pk_bf16(v0[0], v0[1]); w.y = cvt_pk_bf16(v0[2], v0[3]); w.z = cvt_pk_bf16(v1[0], v1[1]); w.w = cvt_pk_bf16(v1[2], v1[3]);
;                     *(u32x4*)(O + ((size_t)((row >> 13) * (ldc >> 3) + ((col0 + bj * HALF) >> 3)) * 8192 + (row & 8191)) * 8) = w; } }
	v_add_f32_e32 v152, v152, v168
	global_store_dwordx4 v[126:127], v[122:125], off sc1
	v_pk_mul_f32 v[118:119], v[118:119], v[158:159] op_sel_hi:[1,0]
	v_fmamk_f32 v152, v152, 0x3a800000, v1
	v_pk_mul_f32 v[122:123], v[116:117], v[158:159] op_sel_hi:[1,0]
	v_pk_mul_f32 v[116:117], v[114:115], v[158:159] op_sel_hi:[1,0]
	v_cvt_pk_bf16_f32 v115, v120, v121
	v_or_b32_e32 v120, 16, v129
	v_cvt_pk_bf16_f32 v114, v118, v119
	v_add_u32_e32 v118, v128, v120
	v_rsq_f32_e32 v152, v152
	v_ashrrev_i32_e32 v119, 31, v118
	v_lshlrev_b64 v[118:119], 17, v[118:119]
	v_lshl_add_u64 v[118:119], s[56:57], 0, v[118:119]
	v_cvt_pk_bf16_f32 v116, v116, v117
	v_cvt_pk_bf16_f32 v117, v122, v123
	v_lshl_add_u64 v[118:119], v[118:119], 0, v[166:167]
	global_store_dwordx4 v[118:119], v[114:117], off sc1
	v_pk_mul_f32 v[110:111], v[110:111], v[152:153] op_sel_hi:[1,0]
	v_pk_mul_f32 v[112:113], v[112:113], v[152:153] op_sel_hi:[1,0]
	v_add_u32_e32 v116, 16, v144
	v_pk_mul_f32 v[114:115], v[108:109], v[152:153] op_sel_hi:[1,0]
	v_pk_mul_f32 v[108:109], v[106:107], v[152:153] op_sel_hi:[1,0]
	v_cvt_pk_bf16_f32 v106, v110, v111
	v_ashrrev_i32_e32 v110, 6, v116
	v_cvt_pk_bf16_f32 v107, v112, v113
	v_and_b32_e32 v112, 0xffffff80, v110
	v_add_u32_e32 v110, v112, v129
	v_ashrrev_i32_e32 v111, 31, v110
	v_lshlrev_b64 v[110:111], 17, v[110:111]
	v_lshlrev_b32_e32 v113, 4, v116
	v_lshl_add_u64 v[110:111], s[56:57], 0, v[110:111]
	v_and_b32_e32 v166, 0x1fff0, v113
	v_cvt_pk_bf16_f32 v108, v108, v109
	v_cvt_pk_bf16_f32 v109, v114, v115
	v_lshl_add_u64 v[110:111], v[110:111], 0, v[166:167]
	v_pk_mul_f32 v[102:103], v[102:103], v[152:153] op_sel_hi:[1,0]
	global_store_dwordx4 v[110:111], v[106:109], off sc1
	v_rsq_f32_e32 v150, v150
	v_pk_mul_f32 v[104:105], v[104:105], v[152:153] op_sel_hi:[1,0]
	v_pk_mul_f32 v[106:107], v[100:101], v[152:153] op_sel_hi:[1,0]
	v_pk_mul_f32 v[100:101], v[98:99], v[152:153] op_sel_hi:[1,0]
	v_cvt_pk_bf16_f32 v98, v102, v103
	v_add_u32_e32 v102, v112, v120
	v_ashrrev_i32_e32 v103, 31, v102
	v_lshlrev_b64 v[102:103], 17, v[102:103]
	v_lshl_add_u64 v[102:103], s[56:57], 0, v[102:103]
	v_cvt_pk_bf16_f32 v99, v104, v105
	v_cvt_pk_bf16_f32 v100, v100, v101
	v_cvt_pk_bf16_f32 v101, v106, v107
	v_lshl_add_u64 v[102:103], v[102:103], 0, v[166:167]
	global_store_dwordx4 v[102:103], v[98:101], off sc1
	v_pk_mul_f32 v[94:95], v[94:95], v[150:151] op_sel_hi:[1,0]
	v_pk_mul_f32 v[96:97], v[96:97], v[150:151] op_sel_hi:[1,0]
	v_add_u32_e32 v100, 32, v144
	v_pk_mul_f32 v[98:99], v[92:93], v[150:151] op_sel_hi:[1,0]
	v_pk_mul_f32 v[92:93], v[90:91], v[150:151] op_sel_hi:[1,0]
	v_cvt_pk_bf16_f32 v90, v94, v95
	v_ashrrev_i32_e32 v94, 6, v100
	v_cvt_pk_bf16_f32 v91, v96, v97
	v_and_b32_e32 v96, 0xffffff80, v94
	v_add_u32_e32 v94, v96, v129
	v_ashrrev_i32_e32 v95, 31, v94
	v_lshlrev_b64 v[94:95], 17, v[94:95]
	v_lshlrev_b32_e32 v97, 4, v100
	v_lshl_add_u64 v[94:95], s[56:57], 0, v[94:95]
	v_and_b32_e32 v166, 0x1fff0, v97
	v_cvt_pk_bf16_f32 v92, v92, v93
	v_cvt_pk_bf16_f32 v93, v98, v99
	v_lshl_add_u64 v[94:95], v[94:95], 0, v[166:167]
	v_pk_mul_f32 v[86:87], v[86:87], v[150:151] op_sel_hi:[1,0]
	v_fmamk_f32 v148, v148, 0x3a800000, v1
	global_store_dwordx4 v[94:95], v[90:93], off sc1
	v_rsq_f32_e32 v148, v148
	v_pk_mul_f32 v[88:89], v[88:89], v[150:151] op_sel_hi:[1,0]
	v_pk_mul_f32 v[90:91], v[84:85], v[150:151] op_sel_hi:[1,0]
	v_pk_mul_f32 v[84:85], v[82:83], v[150:151] op_sel_hi:[1,0]
	v_cvt_pk_bf16_f32 v82, v86, v87
	v_add_u32_e32 v86, v96, v120
	v_ashrrev_i32_e32 v87, 31, v86
	v_lshlrev_b64 v[86:87], 17, v[86:87]
	v_lshl_add_u64 v[86:87], s[56:57], 0, v[86:87]
	v_cvt_pk_bf16_f32 v83, v88, v89
	v_cvt_pk_bf16_f32 v84, v84, v85
	v_cvt_pk_bf16_f32 v85, v90, v91
	v_lshl_add_u64 v[86:87], v[86:87], 0, v[166:167]
	global_store_dwordx4 v[86:87], v[82:85], off sc1
	v_pk_mul_f32 v[78:79], v[78:79], v[148:149] op_sel_hi:[1,0]
	v_pk_mul_f32 v[80:81], v[80:81], v[148:149] op_sel_hi:[1,0]
	v_add_u32_e32 v84, 48, v144
	v_pk_mul_f32 v[82:83], v[76:77], v[148:149] op_sel_hi:[1,0]
	v_pk_mul_f32 v[76:77], v[74:75], v[148:149] op_sel_hi:[1,0]
	v_cvt_pk_bf16_f32 v74, v78, v79
	v_ashrrev_i32_e32 v78, 6, v84
	v_cvt_pk_bf16_f32 v75, v80, v81
	v_and_b32_e32 v80, 0xffffff80, v78
	v_add_u32_e32 v78, v80, v129
	v_ashrrev_i32_e32 v79, 31, v78
	v_lshlrev_b64 v[78:79], 17, v[78:79]
	v_lshlrev_b32_e32 v81, 4, v84
	v_lshl_add_u64 v[78:79], s[56:57], 0, v[78:79]
	v_and_b32_e32 v166, 0x1fff0, v81
	v_cvt_pk_bf16_f32 v76, v76, v77
	v_cvt_pk_bf16_f32 v77, v82, v83
	v_lshl_add_u64 v[78:79], v[78:79], 0, v[166:167]
	v_pk_mul_f32 v[70:71], v[70:71], v[148:149] op_sel_hi:[1,0]
	v_fmamk_f32 v146, v146, 0x3a800000, v1
	global_store_dwordx4 v[78:79], v[74:77], off sc1
	v_rsq_f32_e32 v146, v146
	v_pk_mul_f32 v[72:73], v[72:73], v[148:149] op_sel_hi:[1,0]
	v_pk_mul_f32 v[74:75], v[68:69], v[148:149] op_sel_hi:[1,0]
	v_pk_mul_f32 v[68:69], v[66:67], v[148:149] op_sel_hi:[1,0]
	v_cvt_pk_bf16_f32 v66, v70, v71
	v_add_u32_e32 v70, v80, v120
	v_ashrrev_i32_e32 v71, 31, v70
	v_lshlrev_b64 v[70:71], 17, v[70:71]
	v_lshl_add_u64 v[70:71], s[56:57], 0, v[70:71]
	v_cvt_pk_bf16_f32 v67, v72, v73
	v_cvt_pk_bf16_f32 v68, v68, v69
	v_cvt_pk_bf16_f32 v69, v74, v75
	v_lshl_add_u64 v[70:71], v[70:71], 0, v[166:167]
	global_store_dwordx4 v[70:71], v[66:69], off sc1
	v_pk_mul_f32 v[62:63], v[62:63], v[146:147] op_sel_hi:[1,0]
	v_pk_mul_f32 v[64:65], v[64:65], v[146:147] op_sel_hi:[1,0]
	v_add_u32_e32 v68, 0x80, v144
	v_pk_mul_f32 v[66:67], v[60:61], v[146:147] op_sel_hi:[1,0]
; __device__ __forceinline__ unsigned cvt_pk_bf16(float lo, float hi) { f32x2_t v = {lo, hi}; bf16x2_t b = __builtin_convertvector(v, bf16x2_t); return __builtin_bit_cast(unsigned, b); }
;     __device__ __forceinline__ void operator()(const f32x4 (&acc)[2][2][4][2], const Unit& u, int wr, int wc, int fr, int fq) const {
;     ...
;             for (int m = 0; m < 4; ++m) { const int row = row0 + ai * HALF + m * 16; const float r = rr[ai][m];
; #pragma unroll
;                 for (int bj = 0; bj < 2; ++bj) { const f32x4 v0 = acc[ai][bj][m][0] * r, v1 = acc[ai][bj][m][1] * r;
;                     u32x4 w; w.x = cvt_pk_bf16(v0[0], v0[1]); w.y = cvt_pk_bf16(v0[2], v0[3]); w.z = cvt_pk_bf16(v1[0], v1[1]); w.w = cvt_pk_bf16(v1[2], v1[3]);
;                     *(u32x4*)(O + ((size_t)((row >> 13) * (ldc >> 3) + ((col0 + bj * HALF) >> 3)) * 8192 + (row & 8191)) * 8) = w; } }
	v_pk_mul_f32 v[60:61], v[58:59], v[146:147] op_sel_hi:[1,0]
	v_cvt_pk_bf16_f32 v58, v62, v63
	v_ashrrev_i32_e32 v62, 6, v68
	v_cvt_pk_bf16_f32 v59, v64, v65
	v_and_b32_e32 v64, 0xffffff80, v62
	v_add_u32_e32 v62, v64, v129
	v_ashrrev_i32_e32 v63, 31, v62
	v_lshlrev_b64 v[62:63], 17, v[62:63]
	v_lshlrev_b32_e32 v65, 4, v68
	v_lshl_add_u64 v[62:63], s[56:57], 0, v[62:63]
	v_and_b32_e32 v166, 0x1fff0, v65
	v_cvt_pk_bf16_f32 v60, v60, v61
	v_cvt_pk_bf16_f32 v61, v66, v67
	v_lshl_add_u64 v[62:63], v[62:63], 0, v[166:167]
	v_pk_mul_f32 v[54:55], v[54:55], v[146:147] op_sel_hi:[1,0]
	global_store_dwordx4 v[62:63], v[58:61], off sc1
	v_pk_mul_f32 v[56:57], v[56:57], v[146:147] op_sel_hi:[1,0]
	v_pk_mul_f32 v[46:47], v[46:47], v[160:161] op_sel_hi:[1,0]
	v_pk_mul_f32 v[58:59], v[52:53], v[146:147] op_sel_hi:[1,0]
	v_pk_mul_f32 v[52:53], v[50:51], v[146:147] op_sel_hi:[1,0]
	v_cvt_pk_bf16_f32 v50, v54, v55
	v_add_u32_e32 v54, v64, v120
	v_ashrrev_i32_e32 v55, 31, v54
	v_lshlrev_b64 v[54:55], 17, v[54:55]
	v_lshl_add_u64 v[54:55], s[56:57], 0, v[54:55]
	v_cvt_pk_bf16_f32 v51, v56, v57
	v_cvt_pk_bf16_f32 v52, v52, v53
	v_cvt_pk_bf16_f32 v53, v58, v59
	v_lshl_add_u64 v[54:55], v[54:55], 0, v[166:167]
	global_store_dwordx4 v[54:55], v[50:53], off sc1
	v_pk_mul_f32 v[48:49], v[48:49], v[160:161] op_sel_hi:[1,0]
	v_pk_mul_f32 v[38:39], v[38:39], v[160:161] op_sel_hi:[1,0]
	v_add_u32_e32 v52, 0x90, v144
	v_pk_mul_f32 v[50:51], v[44:45], v[160:161] op_sel_hi:[1,0]
	v_pk_mul_f32 v[44:45], v[42:43], v[160:161] op_sel_hi:[1,0]
	v_cvt_pk_bf16_f32 v42, v46, v47
	v_ashrrev_i32_e32 v46, 6, v52
	v_cvt_pk_bf16_f32 v43, v48, v49
	v_and_b32_e32 v48, 0xffffff80, v46
	v_add_u32_e32 v46, v48, v129
	v_ashrrev_i32_e32 v47, 31, v46
	v_lshlrev_b64 v[46:47], 17, v[46:47]
	v_lshlrev_b32_e32 v49, 4, v52
	v_lshl_add_u64 v[46:47], s[56:57], 0, v[46:47]
	v_and_b32_e32 v166, 0x1fff0, v49
	v_cvt_pk_bf16_f32 v44, v44, v45
	v_cvt_pk_bf16_f32 v45, v50, v51
	v_lshl_add_u64 v[46:47], v[46:47], 0, v[166:167]
	global_store_dwordx4 v[46:47], v[42:45], off sc1
	v_pk_mul_f32 v[40:41], v[40:41], v[160:161] op_sel_hi:[1,0]
	v_pk_mul_f32 v[30:31], v[30:31], v[154:155] op_sel_hi:[1,0]
	v_pk_mul_f32 v[42:43], v[36:37], v[160:161] op_sel_hi:[1,0]
	v_pk_mul_f32 v[36:37], v[34:35], v[160:161] op_sel_hi:[1,0]
	v_cvt_pk_bf16_f32 v34, v38, v39
	v_add_u32_e32 v38, v48, v120
	v_ashrrev_i32_e32 v39, 31, v38
	v_lshlrev_b64 v[38:39], 17, v[38:39]
	v_lshl_add_u64 v[38:39], s[56:57], 0, v[38:39]
	v_cvt_pk_bf16_f32 v35, v40, v41
	v_cvt_pk_bf16_f32 v36, v36, v37
	v_cvt_pk_bf16_f32 v37, v42, v43
	v_lshl_add_u64 v[38:39], v[38:39], 0, v[166:167]
	global_store_dwordx4 v[38:39], v[34:37], off sc1
	v_pk_mul_f32 v[32:33], v[32:33], v[154:155] op_sel_hi:[1,0]
	v_pk_mul_f32 v[22:23], v[22:23], v[154:155] op_sel_hi:[1,0]
	v_add_u32_e32 v36, 0xa0, v144
	v_pk_mul_f32 v[34:35], v[28:29], v[154:155] op_sel_hi:[1,0]
	v_pk_mul_f32 v[28:29], v[26:27], v[154:155] op_sel_hi:[1,0]
	v_cvt_pk_bf16_f32 v26, v30, v31
	v_ashrrev_i32_e32 v30, 6, v36
	v_cvt_pk_bf16_f32 v27, v32, v33
	v_and_b32_e32 v32, 0xffffff80, v30
	v_add_u32_e32 v30, v32, v129
	v_ashrrev_i32_e32 v31, 31, v30
	v_lshlrev_b64 v[30:31], 17, v[30:31]
	v_lshlrev_b32_e32 v33, 4, v36
	v_lshl_add_u64 v[30:31], s[56:57], 0, v[30:31]
	v_and_b32_e32 v166, 0x1fff0, v33
	v_cvt_pk_bf16_f32 v28, v28, v29
	v_cvt_pk_bf16_f32 v29, v34, v35
	v_lshl_add_u64 v[30:31], v[30:31], 0, v[166:167]
	global_store_dwordx4 v[30:31], v[26:29], off sc1
	v_pk_mul_f32 v[24:25], v[24:25], v[154:155] op_sel_hi:[1,0]
	v_pk_mul_f32 v[14:15], v[14:15], v[156:157] op_sel_hi:[1,0]
	v_pk_mul_f32 v[26:27], v[20:21], v[154:155] op_sel_hi:[1,0]
	v_pk_mul_f32 v[20:21], v[18:19], v[154:155] op_sel_hi:[1,0]
	v_cvt_pk_bf16_f32 v18, v22, v23
	v_add_u32_e32 v22, v32, v120
	v_ashrrev_i32_e32 v23, 31, v22
	v_lshlrev_b64 v[22:23], 17, v[22:23]
	v_lshl_add_u64 v[22:23], s[56:57], 0, v[22:23]
	v_cvt_pk_bf16_f32 v19, v24, v25
	v_cvt_pk_bf16_f32 v20, v20, v21
	v_cvt_pk_bf16_f32 v21, v26, v27
	v_lshl_add_u64 v[22:23], v[22:23], 0, v[166:167]
	global_store_dwordx4 v[22:23], v[18:21], off sc1
	v_pk_mul_f32 v[16:17], v[16:17], v[156:157] op_sel_hi:[1,0]
	v_pk_mul_f32 v[6:7], v[6:7], v[156:157] op_sel_hi:[1,0]
	v_add_u32_e32 v20, 0xb0, v144
	v_pk_mul_f32 v[18:19], v[12:13], v[156:157] op_sel_hi:[1,0]
	v_pk_mul_f32 v[12:13], v[10:11], v[156:157] op_sel_hi:[1,0]
	v_cvt_pk_bf16_f32 v10, v14, v15
	v_ashrrev_i32_e32 v14, 6, v20
	v_cvt_pk_bf16_f32 v11, v16, v17
	v_and_b32_e32 v16, 0xffffff80, v14
	v_add_u32_e32 v14, v16, v129
	v_ashrrev_i32_e32 v15, 31, v14
	v_lshlrev_b64 v[14:15], 17, v[14:15]
	v_lshlrev_b32_e32 v17, 4, v20
	v_lshl_add_u64 v[14:15], s[56:57], 0, v[14:15]
	v_and_b32_e32 v166, 0x1fff0, v17
	v_cvt_pk_bf16_f32 v12, v12, v13
	v_cvt_pk_bf16_f32 v13, v18, v19
	v_lshl_add_u64 v[14:15], v[14:15], 0, v[166:167]
	global_store_dwordx4 v[14:15], v[10:13], off sc1
	v_pk_mul_f32 v[8:9], v[8:9], v[156:157] op_sel_hi:[1,0]
	s_nop 0
	v_pk_mul_f32 v[10:11], v[4:5], v[156:157] op_sel_hi:[1,0]
	v_pk_mul_f32 v[4:5], v[2:3], v[156:157] op_sel_hi:[1,0]
	v_cvt_pk_bf16_f32 v2, v6, v7
	v_add_u32_e32 v6, v16, v120
	v_ashrrev_i32_e32 v7, 31, v6
	v_lshlrev_b64 v[6:7], 17, v[6:7]
	v_lshl_add_u64 v[6:7], s[56:57], 0, v[6:7]
	v_cvt_pk_bf16_f32 v3, v8, v9
	v_cvt_pk_bf16_f32 v4, v4, v5
	v_cvt_pk_bf16_f32 v5, v10, v11
	v_lshl_add_u64 v[6:7], v[6:7], 0, v[166:167]
	global_store_dwordx4 v[6:7], v[2:5], off sc1
	s_cbranch_vccnz .LBB0_118
	s_andn2_b64 vcc, exec, s[60:61]
	s_cbranch_vccnz .LBB0_117
	s_barrier
	s_branch .LBB0_117

; __device__ __forceinline__ unsigned cvt_pk_bf16(float lo, float hi) { f32x2_t v = {lo, hi}; bf16x2_t b = __builtin_convertvector(v, bf16x2_t); return __builtin_bit_cast(unsigned, b); }
; #define GAS __attribute__((address_space(1)))
; #define LAS __attribute__((address_space(3)))
; __device__ __forceinline__ void fft_phase(Frame& F, const bf16* Yc, bf16* Y) {
;     ...
;         for (int i = 0; i < 16; ++i) { const int k = t + 512 * i, km = (SEQ - k) & (SEQ - 1);
;             const v4u v = *(const LAS v4u*)(buf + fft_slot(k)), w = *(const LAS v4u*)(buf + fft_slot(km));
;             float d0 = bflo(v.x) * sc1, m0 = bflo(w.x) * sc1;
;             if (q4 == 0) { d0 = 0.5f * sc1 * (bflo(v.x) + bflo(w.x)); m0 = 0.5f * sc1 * (bfhi(v.x) + bfhi(w.x)); }
;             bf16* row = dst + (size_t)k * 1024;
;             v2u o; o.x = pg8::cvt_pk_bf16(d0, bflo(v.y) * sc1); o.y = pg8::cvt_pk_bf16(bflo(v.z) * sc1, bflo(v.w) * sc1);
;             *(GAS v2u*)(row + 4 * q4) = o;
;             const unsigned m12 = pg8::cvt_pk_bf16(bflo(w.z) * sc1, bflo(w.y) * sc1);
;             const unsigned m3 = pg8::cvt_pk_bf16(bflo(w.w) * sc1, 0.f) & 0xffffu, mz = pg8::cvt_pk_bf16(m0, 0.f) & 0xffffu;
;             if (q4 != 0) { P8u o2; o2.a = m3 | (m12 << 16); o2.b = (m12 >> 16) | (mz << 16); *(P8u*)(row + 125 - 4 * q4) = o2; }
;             else { row[125] = (bf16)m3; *(GAS unsigned*)(row + 126) = m12; row[64] = (bf16)mz; }
.LBB0_207:
	v_lshlrev_b32_e32 v2, 16, v7
	v_lshlrev_b32_e32 v9, 16, v9
	v_lshlrev_b32_e32 v8, 16, v8
	v_mul_f32_e32 v2, 0x3a800000, v2
	v_pk_mul_f32 v[8:9], v[8:9], s[64:65] op_sel_hi:[1,0]
	v_cvt_pk_bf16_f32 v6, v144, v2
	v_cvt_pk_bf16_f32 v7, v8, v9
	v_lshlrev_b32_e32 v147, 16, v4
	v_lshlrev_b32_e32 v146, 16, v3
	v_pk_mul_f32 v[2:3], v[146:147], s[64:65] op_sel_hi:[1,0]
	s_nop 0
	v_pk_mov_b32 v[2:3], v[2:3], v[2:3] op_sel:[1,0]
	v_cvt_pk_bf16_f32 v3, v2, v3
	v_lshlrev_b32_e32 v2, 16, v5
	v_mul_f32_e32 v2, 0x3a800000, v2
	v_cvt_pk_bf16_f32 v4, v2, 0
	v_cvt_pk_bf16_f32 v2, v145, 0
	v_and_b32_e32 v5, 0xffff, v4
	v_lshl_or_b32 v8, v3, 16, v5
	v_alignbit_b32 v9, v2, v3, 16
	v_lshlrev_b32_e32 v152, 4, v148
	v_mov_b32_e32 v153, 0
	v_lshl_add_u64 v[152:153], s[4:5], 0, v[152:153]
	global_store_dwordx4 v[152:153], v[6:9], off sc1

; __device__ __forceinline__ unsigned cvt_pk_bf16(float lo, float hi) { f32x2_t v = {lo, hi}; bf16x2_t b = __builtin_convertvector(v, bf16x2_t); return __builtin_bit_cast(unsigned, b); }
; #define GAS __attribute__((address_space(1)))
; #define LAS __attribute__((address_space(3)))
; __device__ __forceinline__ void fft_phase(Frame& F, const bf16* Yc, bf16* Y) {
;     ...
;         for (int i = 0; i < 16; ++i) { const int k = t + 512 * i, km = (SEQ - k) & (SEQ - 1);
;             const v4u v = *(const LAS v4u*)(buf + fft_slot(k)), w = *(const LAS v4u*)(buf + fft_slot(km));
;             float d0 = bflo(v.x) * sc1, m0 = bflo(w.x) * sc1;
;             if (q4 == 0) { d0 = 0.5f * sc1 * (bflo(v.x) + bflo(w.x)); m0 = 0.5f * sc1 * (bfhi(v.x) + bfhi(w.x)); }
;             bf16* row = dst + (size_t)k * 1024;
;             v2u o; o.x = pg8::cvt_pk_bf16(d0, bflo(v.y) * sc1); o.y = pg8::cvt_pk_bf16(bflo(v.z) * sc1, bflo(v.w) * sc1);
;             *(GAS v2u*)(row + 4 * q4) = o;
;             const unsigned m12 = pg8::cvt_pk_bf16(bflo(w.z) * sc1, bflo(w.y) * sc1);
;             const unsigned m3 = pg8::cvt_pk_bf16(bflo(w.w) * sc1, 0.f) & 0xffffu, mz = pg8::cvt_pk_bf16(m0, 0.f) & 0xffffu;
;             if (q4 != 0) { P8u o2; o2.a = m3 | (m12 << 16); o2.b = (m12 >> 16) | (mz << 16); *(P8u*)(row + 125 - 4 * q4) = o2; }
;             else { row[125] = (bf16)m3; *(GAS unsigned*)(row + 126) = m12; row[64] = (bf16)mz; }
.LBB0_214:
	v_ashrrev_i32_e32 v145, 31, v144
	v_lshlrev_b64 v[144:145], 4, v[144:145]
	v_lshlrev_b32_e32 v2, 16, v7
	v_lshlrev_b32_e32 v9, 16, v9
	v_lshlrev_b32_e32 v8, 16, v8
	v_lshl_add_u64 v[144:145], s[4:5], 0, v[144:145]
	v_mul_f32_e32 v2, 0x3a800000, v2
	v_pk_mul_f32 v[8:9], v[8:9], s[64:65] op_sel_hi:[1,0]
	v_cvt_pk_bf16_f32 v6, v146, v2
	v_cvt_pk_bf16_f32 v7, v8, v9
	v_lshlrev_b32_e32 v151, 16, v4
	v_lshlrev_b32_e32 v150, 16, v3
	v_pk_mul_f32 v[2:3], v[150:151], s[64:65] op_sel_hi:[1,0]
	s_nop 0
	v_pk_mov_b32 v[2:3], v[2:3], v[2:3] op_sel:[1,0]
	v_cvt_pk_bf16_f32 v2, v2, v3
	v_lshlrev_b32_e32 v3, 16, v5
	v_mul_f32_e32 v3, 0x3a800000, v3
	v_cvt_pk_bf16_f32 v4, v3, 0
	v_cvt_pk_bf16_f32 v3, v147, 0
	v_and_b32_e32 v5, 0xffff, v4
	v_lshl_or_b32 v8, v2, 16, v5
	v_alignbit_b32 v9, v3, v2, 16
	v_mov_b64_e32 v[150:151], v[144:145]
	global_store_dwordx4 v[150:151], v[6:9], off sc1
	s_branch .LBB0_203
